# f32 GEMM epilogues: group wait split into vmcnt(6) at the first chunk and vmcnt(4) at the third (waits at first consumer)
# speedup vs baseline: 1.0059x; 1.0059x over previous
.LBB0_95:
	v_lshl_or_b32 v170, s82, 8, v176
	v_lshl_add_u32 v172, s81, 8, v174
	v_ashrrev_i32_e32 v171, 31, v170
	v_ashrrev_i32_e32 v173, 31, v172
	v_lshlrev_b64 v[48:49], 2, v[170:171]
	v_lshlrev_b64 v[178:179], 10, v[172:173]
	v_lshl_add_u64 v[52:53], s[50:51], 0, v[48:49]
	v_lshl_add_u64 v[60:61], s[52:53], 0, v[48:49]
	v_lshl_add_u64 v[178:179], v[178:179], 0, v[170:171]
	v_lshl_add_u64 v[180:181], v[172:173], 3, s[14:15]
	global_load_dwordx4 v[64:67], v[52:53], off offset:16
	global_load_dwordx4 v[72:75], v[52:53], off
	global_load_dwordx4 v[68:71], v[60:61], off offset:16
	global_load_dwordx4 v[76:79], v[60:61], off
	global_load_dwordx4 v[48:51], v[52:53], off offset:528
	global_load_dwordx4 v[56:59], v[52:53], off offset:512
	s_nop 0
	global_load_dwordx4 v[52:55], v[60:61], off offset:528
	s_nop 0
	global_load_dwordx4 v[60:63], v[60:61], off offset:512
	v_lshlrev_b64 v[198:199], 2, v[178:179]
	global_load_dwordx2 v[190:191], v[180:181], off
	v_lshl_add_u64 v[194:195], s[44:45], 0, v[198:199]
	global_load_dwordx4 v[178:181], v[194:195], off offset:16
	global_load_dwordx4 v[182:185], v[194:195], off
	global_load_dwordx4 v[186:189], v[194:195], off offset:528
	s_nop 0
	global_load_dwordx4 v[194:197], v[194:195], off offset:512
	s_mov_b64 s[28:29], -1
	s_and_b64 vcc, exec, s[40:41]
	s_waitcnt vmcnt(0)
	v_sub_f32_e32 v183, v183, v190
	v_sub_f32_e32 v182, v182, v190
	v_sub_f32_e32 v185, v185, v190
	v_sub_f32_e32 v184, v184, v190
	v_pk_mul_f32 v[184:185], v[190:191], v[184:185] op_sel:[1,0]
	v_pk_mul_f32 v[182:183], v[190:191], v[182:183] op_sel:[1,0]
	v_pk_fma_f32 v[184:185], v[74:75], v[184:185], v[78:79]
	v_pk_fma_f32 v[182:183], v[72:73], v[182:183], v[76:77]
	v_pk_fma_f32 v[158:159], v[184:185], s[22:23], v[158:159] op_sel_hi:[1,0,1]
	v_pk_fma_f32 v[156:157], v[182:183], s[22:23], v[156:157] op_sel_hi:[1,0,1]
	v_lshl_add_u64 v[182:183], s[46:47], 0, v[198:199]
	global_store_dwordx4 v[182:183], v[156:159], off
	s_nop 1
	v_sub_f32_e32 v157, v179, v190
	v_sub_f32_e32 v156, v178, v190
	v_sub_f32_e32 v159, v181, v190
	v_sub_f32_e32 v158, v180, v190
	v_pk_mul_f32 v[158:159], v[190:191], v[158:159] op_sel:[1,0]
	v_pk_mul_f32 v[156:157], v[190:191], v[156:157] op_sel:[1,0]
	v_pk_fma_f32 v[158:159], v[66:67], v[158:159], v[70:71]
	v_pk_fma_f32 v[156:157], v[64:65], v[156:157], v[68:69]
	v_pk_fma_f32 v[154:155], v[158:159], s[22:23], v[154:155] op_sel_hi:[1,0,1]
	v_pk_fma_f32 v[152:153], v[156:157], s[22:23], v[152:153] op_sel_hi:[1,0,1]
	global_store_dwordx4 v[182:183], v[152:155], off offset:16
	s_nop 1
	v_sub_f32_e32 v153, v195, v190
	v_sub_f32_e32 v152, v194, v190
	v_sub_f32_e32 v155, v197, v190
	v_sub_f32_e32 v154, v196, v190
	v_pk_mul_f32 v[154:155], v[190:191], v[154:155] op_sel:[1,0]
	v_pk_mul_f32 v[152:153], v[190:191], v[152:153] op_sel:[1,0]
	v_pk_fma_f32 v[154:155], v[58:59], v[154:155], v[62:63]
	v_pk_fma_f32 v[152:153], v[56:57], v[152:153], v[60:61]
	v_pk_fma_f32 v[150:151], v[154:155], s[22:23], v[150:151] op_sel_hi:[1,0,1]
	v_pk_fma_f32 v[148:149], v[152:153], s[22:23], v[148:149] op_sel_hi:[1,0,1]
	global_store_dwordx4 v[182:183], v[148:151], off offset:512
	s_nop 1
	v_sub_f32_e32 v149, v187, v190
	v_sub_f32_e32 v148, v186, v190
	v_sub_f32_e32 v151, v189, v190
	v_sub_f32_e32 v150, v188, v190
	v_pk_mul_f32 v[150:151], v[190:191], v[150:151] op_sel:[1,0]
	v_pk_mul_f32 v[148:149], v[190:191], v[148:149] op_sel:[1,0]
	v_pk_fma_f32 v[150:151], v[50:51], v[150:151], v[54:55]
	v_pk_fma_f32 v[148:149], v[48:49], v[148:149], v[52:53]
	v_pk_fma_f32 v[146:147], v[150:151], s[22:23], v[146:147] op_sel_hi:[1,0,1]
	v_pk_fma_f32 v[144:145], v[148:149], s[22:23], v[144:145] op_sel_hi:[1,0,1]
	global_store_dwordx4 v[182:183], v[144:147], off offset:528
	s_nop 1
	v_or_b32_e32 v144, 16, v172
	v_ashrrev_i32_e32 v145, 31, v144
	v_lshlrev_b64 v[146:147], 10, v[144:145]
	v_lshl_add_u64 v[146:147], v[146:147], 0, v[170:171]
	v_lshl_add_u64 v[144:145], v[144:145], 3, s[14:15]
	global_load_dwordx2 v[178:179], v[144:145], off
	v_lshlrev_b64 v[180:181], 2, v[146:147]
	v_lshl_add_u64 v[156:157], s[44:45], 0, v[180:181]
	global_load_dwordx4 v[144:147], v[156:157], off offset:16
	global_load_dwordx4 v[148:151], v[156:157], off
	global_load_dwordx4 v[152:155], v[156:157], off offset:528
	s_nop 0
	global_load_dwordx4 v[156:159], v[156:157], off offset:512
	s_waitcnt vmcnt(0)
	v_sub_f32_e32 v149, v149, v178
	v_sub_f32_e32 v148, v148, v178
	v_sub_f32_e32 v151, v151, v178
	v_sub_f32_e32 v150, v150, v178
	v_pk_mul_f32 v[150:151], v[178:179], v[150:151] op_sel:[1,0]
	v_pk_mul_f32 v[148:149], v[178:179], v[148:149] op_sel:[1,0]
	v_pk_fma_f32 v[150:151], v[74:75], v[150:151], v[78:79]
	v_pk_fma_f32 v[148:149], v[72:73], v[148:149], v[76:77]
	v_pk_fma_f32 v[142:143], v[150:151], s[22:23], v[142:143] op_sel_hi:[1,0,1]
	v_pk_fma_f32 v[140:141], v[148:149], s[22:23], v[140:141] op_sel_hi:[1,0,1]
	v_sub_f32_e32 v145, v145, v178
	v_sub_f32_e32 v144, v144, v178
	v_sub_f32_e32 v147, v147, v178
	v_sub_f32_e32 v146, v146, v178
	v_pk_mul_f32 v[146:147], v[178:179], v[146:147] op_sel:[1,0]
	v_pk_mul_f32 v[144:145], v[178:179], v[144:145] op_sel:[1,0]
	v_pk_fma_f32 v[146:147], v[66:67], v[146:147], v[70:71]
	v_pk_fma_f32 v[144:145], v[64:65], v[144:145], v[68:69]
	v_pk_fma_f32 v[138:139], v[146:147], s[22:23], v[138:139] op_sel_hi:[1,0,1]
	v_pk_fma_f32 v[136:137], v[144:145], s[22:23], v[136:137] op_sel_hi:[1,0,1]
	v_sub_f32_e32 v157, v157, v178
	v_sub_f32_e32 v156, v156, v178
	v_sub_f32_e32 v159, v159, v178
	v_sub_f32_e32 v158, v158, v178
	v_pk_mul_f32 v[158:159], v[178:179], v[158:159] op_sel:[1,0]
	v_pk_mul_f32 v[156:157], v[178:179], v[156:157] op_sel:[1,0]
	v_pk_fma_f32 v[158:159], v[58:59], v[158:159], v[62:63]
	v_pk_fma_f32 v[156:157], v[56:57], v[156:157], v[60:61]
	v_pk_fma_f32 v[134:135], v[158:159], s[22:23], v[134:135] op_sel_hi:[1,0,1]
	v_pk_fma_f32 v[132:133], v[156:157], s[22:23], v[132:133] op_sel_hi:[1,0,1]
	v_sub_f32_e32 v153, v153, v178
	v_sub_f32_e32 v152, v152, v178
	v_sub_f32_e32 v155, v155, v178
	v_sub_f32_e32 v154, v154, v178
	v_pk_mul_f32 v[154:155], v[178:179], v[154:155] op_sel:[1,0]
	v_pk_mul_f32 v[152:153], v[178:179], v[152:153] op_sel:[1,0]
	v_pk_fma_f32 v[154:155], v[50:51], v[154:155], v[54:55]
	v_pk_fma_f32 v[152:153], v[48:49], v[152:153], v[52:53]
	v_pk_fma_f32 v[130:131], v[154:155], s[22:23], v[130:131] op_sel_hi:[1,0,1]
	v_pk_fma_f32 v[128:129], v[152:153], s[22:23], v[128:129] op_sel_hi:[1,0,1]
	v_lshl_add_u64 v[248:249], s[46:47], 0, v[180:181]
	v_or_b32_e32 v206, 32, v172
	v_ashrrev_i32_e32 v207, 31, v206
	v_lshlrev_b64 v[208:209], 10, v[206:207]
	v_lshl_add_u64 v[208:209], v[208:209], 0, v[170:171]
	v_lshl_add_u64 v[206:207], v[206:207], 3, s[14:15]
	global_load_dwordx2 v[250:251], v[206:207], off
	v_lshlrev_b64 v[246:247], 2, v[208:209]
	v_lshl_add_u64 v[208:209], s[44:45], 0, v[246:247]
	global_load_dwordx4 v[144:147], v[208:209], off offset:16
	global_load_dwordx4 v[148:151], v[208:209], off
	global_load_dwordx4 v[152:155], v[208:209], off offset:528
	global_load_dwordx4 v[156:159], v[208:209], off offset:512
	global_store_dwordx4 v[248:249], v[140:143], off
	global_store_dwordx4 v[248:249], v[136:139], off offset:16
	global_store_dwordx4 v[248:249], v[132:135], off offset:512
	global_store_dwordx4 v[248:249], v[128:131], off offset:528
	s_waitcnt vmcnt(6)
	v_sub_f32_e32 v149, v149, v250
	v_sub_f32_e32 v148, v148, v250
	v_sub_f32_e32 v151, v151, v250
	v_sub_f32_e32 v150, v150, v250
	v_pk_mul_f32 v[150:151], v[250:251], v[150:151] op_sel:[1,0]
	v_pk_mul_f32 v[148:149], v[250:251], v[148:149] op_sel:[1,0]
	v_pk_fma_f32 v[150:151], v[74:75], v[150:151], v[78:79]
	v_pk_fma_f32 v[148:149], v[72:73], v[148:149], v[76:77]
	v_pk_fma_f32 v[126:127], v[150:151], s[22:23], v[126:127] op_sel_hi:[1,0,1]
	v_pk_fma_f32 v[124:125], v[148:149], s[22:23], v[124:125] op_sel_hi:[1,0,1]
	v_sub_f32_e32 v145, v145, v250
	v_sub_f32_e32 v144, v144, v250
	v_sub_f32_e32 v147, v147, v250
	v_sub_f32_e32 v146, v146, v250
	v_pk_mul_f32 v[146:147], v[250:251], v[146:147] op_sel:[1,0]
	v_pk_mul_f32 v[144:145], v[250:251], v[144:145] op_sel:[1,0]
	v_pk_fma_f32 v[146:147], v[66:67], v[146:147], v[70:71]
	v_pk_fma_f32 v[144:145], v[64:65], v[144:145], v[68:69]
	v_pk_fma_f32 v[122:123], v[146:147], s[22:23], v[122:123] op_sel_hi:[1,0,1]
	v_pk_fma_f32 v[120:121], v[144:145], s[22:23], v[120:121] op_sel_hi:[1,0,1]
	s_waitcnt vmcnt(4)
	v_sub_f32_e32 v157, v157, v250
	v_sub_f32_e32 v156, v156, v250
	v_sub_f32_e32 v159, v159, v250
	v_sub_f32_e32 v158, v158, v250
	v_pk_mul_f32 v[158:159], v[250:251], v[158:159] op_sel:[1,0]
	v_pk_mul_f32 v[156:157], v[250:251], v[156:157] op_sel:[1,0]
	v_pk_fma_f32 v[158:159], v[58:59], v[158:159], v[62:63]
	v_pk_fma_f32 v[156:157], v[56:57], v[156:157], v[60:61]
	v_pk_fma_f32 v[118:119], v[158:159], s[22:23], v[118:119] op_sel_hi:[1,0,1]
	v_pk_fma_f32 v[116:117], v[156:157], s[22:23], v[116:117] op_sel_hi:[1,0,1]
	v_sub_f32_e32 v153, v153, v250
	v_sub_f32_e32 v152, v152, v250
	v_sub_f32_e32 v155, v155, v250
	v_sub_f32_e32 v154, v154, v250
	v_pk_mul_f32 v[154:155], v[250:251], v[154:155] op_sel:[1,0]
	v_pk_mul_f32 v[152:153], v[250:251], v[152:153] op_sel:[1,0]
	v_pk_fma_f32 v[154:155], v[50:51], v[154:155], v[54:55]
	v_pk_fma_f32 v[152:153], v[48:49], v[152:153], v[52:53]
	v_pk_fma_f32 v[114:115], v[154:155], s[22:23], v[114:115] op_sel_hi:[1,0,1]
	v_pk_fma_f32 v[112:113], v[152:153], s[22:23], v[112:113] op_sel_hi:[1,0,1]
	v_lshl_add_u64 v[248:249], s[46:47], 0, v[246:247]
	v_or_b32_e32 v206, 48, v172
	v_ashrrev_i32_e32 v207, 31, v206
	v_lshlrev_b64 v[208:209], 10, v[206:207]
	v_lshl_add_u64 v[208:209], v[208:209], 0, v[170:171]
	v_lshl_add_u64 v[206:207], v[206:207], 3, s[14:15]
	global_load_dwordx2 v[250:251], v[206:207], off
	v_lshlrev_b64 v[246:247], 2, v[208:209]
	v_lshl_add_u64 v[208:209], s[44:45], 0, v[246:247]
	global_load_dwordx4 v[144:147], v[208:209], off offset:16
	global_load_dwordx4 v[148:151], v[208:209], off
	global_load_dwordx4 v[152:155], v[208:209], off offset:528
	global_load_dwordx4 v[156:159], v[208:209], off offset:512
	global_store_dwordx4 v[248:249], v[124:127], off
	global_store_dwordx4 v[248:249], v[120:123], off offset:16
	global_store_dwordx4 v[248:249], v[116:119], off offset:512
	global_store_dwordx4 v[248:249], v[112:115], off offset:528
	s_waitcnt vmcnt(6)
	v_sub_f32_e32 v149, v149, v250
	v_sub_f32_e32 v148, v148, v250
	v_sub_f32_e32 v151, v151, v250
	v_sub_f32_e32 v150, v150, v250
	v_pk_mul_f32 v[150:151], v[250:251], v[150:151] op_sel:[1,0]
	v_pk_mul_f32 v[148:149], v[250:251], v[148:149] op_sel:[1,0]
	v_pk_fma_f32 v[150:151], v[74:75], v[150:151], v[78:79]
	v_pk_fma_f32 v[148:149], v[72:73], v[148:149], v[76:77]
	v_pk_fma_f32 v[110:111], v[150:151], s[22:23], v[110:111] op_sel_hi:[1,0,1]
	v_pk_fma_f32 v[108:109], v[148:149], s[22:23], v[108:109] op_sel_hi:[1,0,1]
	v_sub_f32_e32 v145, v145, v250
	v_sub_f32_e32 v144, v144, v250
	v_sub_f32_e32 v147, v147, v250
	v_sub_f32_e32 v146, v146, v250
	v_pk_mul_f32 v[146:147], v[250:251], v[146:147] op_sel:[1,0]
	v_pk_mul_f32 v[144:145], v[250:251], v[144:145] op_sel:[1,0]
	v_pk_fma_f32 v[146:147], v[66:67], v[146:147], v[70:71]
	v_pk_fma_f32 v[144:145], v[64:65], v[144:145], v[68:69]
	v_pk_fma_f32 v[106:107], v[146:147], s[22:23], v[106:107] op_sel_hi:[1,0,1]
	v_pk_fma_f32 v[104:105], v[144:145], s[22:23], v[104:105] op_sel_hi:[1,0,1]
	s_waitcnt vmcnt(4)
	v_sub_f32_e32 v157, v157, v250
	v_sub_f32_e32 v156, v156, v250
	v_sub_f32_e32 v159, v159, v250
	v_sub_f32_e32 v158, v158, v250
	v_pk_mul_f32 v[158:159], v[250:251], v[158:159] op_sel:[1,0]
	v_pk_mul_f32 v[156:157], v[250:251], v[156:157] op_sel:[1,0]
	v_pk_fma_f32 v[158:159], v[58:59], v[158:159], v[62:63]
	v_pk_fma_f32 v[156:157], v[56:57], v[156:157], v[60:61]
	v_pk_fma_f32 v[102:103], v[158:159], s[22:23], v[102:103] op_sel_hi:[1,0,1]
	v_pk_fma_f32 v[100:101], v[156:157], s[22:23], v[100:101] op_sel_hi:[1,0,1]
	v_sub_f32_e32 v153, v153, v250
	v_sub_f32_e32 v152, v152, v250
	v_sub_f32_e32 v155, v155, v250
	v_sub_f32_e32 v154, v154, v250
	v_pk_mul_f32 v[154:155], v[250:251], v[154:155] op_sel:[1,0]
	v_pk_mul_f32 v[152:153], v[250:251], v[152:153] op_sel:[1,0]
	v_pk_fma_f32 v[154:155], v[50:51], v[154:155], v[54:55]
	v_pk_fma_f32 v[152:153], v[48:49], v[152:153], v[52:53]
	v_pk_fma_f32 v[98:99], v[154:155], s[22:23], v[98:99] op_sel_hi:[1,0,1]
	v_pk_fma_f32 v[96:97], v[152:153], s[22:23], v[96:97] op_sel_hi:[1,0,1]
	v_lshl_add_u64 v[248:249], s[46:47], 0, v[246:247]
	v_add_u32_e32 v206, 0x80, v172
	v_ashrrev_i32_e32 v207, 31, v206
	v_lshlrev_b64 v[208:209], 10, v[206:207]
	v_lshl_add_u64 v[208:209], v[208:209], 0, v[170:171]
	v_lshl_add_u64 v[206:207], v[206:207], 3, s[14:15]
	global_load_dwordx2 v[250:251], v[206:207], off
	v_lshlrev_b64 v[246:247], 2, v[208:209]
	v_lshl_add_u64 v[208:209], s[44:45], 0, v[246:247]
	global_load_dwordx4 v[144:147], v[208:209], off offset:16
	global_load_dwordx4 v[148:151], v[208:209], off
	global_load_dwordx4 v[152:155], v[208:209], off offset:528
	global_load_dwordx4 v[156:159], v[208:209], off offset:512
	global_store_dwordx4 v[248:249], v[108:111], off
	global_store_dwordx4 v[248:249], v[104:107], off offset:16
	global_store_dwordx4 v[248:249], v[100:103], off offset:512
	global_store_dwordx4 v[248:249], v[96:99], off offset:528
	s_waitcnt vmcnt(6)
	v_sub_f32_e32 v149, v149, v250
	v_sub_f32_e32 v148, v148, v250
	v_sub_f32_e32 v151, v151, v250
	v_sub_f32_e32 v150, v150, v250
	v_pk_mul_f32 v[150:151], v[250:251], v[150:151] op_sel:[1,0]
	v_pk_mul_f32 v[148:149], v[250:251], v[148:149] op_sel:[1,0]
	v_pk_fma_f32 v[150:151], v[74:75], v[150:151], v[78:79]
	v_pk_fma_f32 v[148:149], v[72:73], v[148:149], v[76:77]
	v_pk_fma_f32 v[94:95], v[150:151], s[22:23], v[94:95] op_sel_hi:[1,0,1]
	v_pk_fma_f32 v[92:93], v[148:149], s[22:23], v[92:93] op_sel_hi:[1,0,1]
	v_sub_f32_e32 v145, v145, v250
	v_sub_f32_e32 v144, v144, v250
	v_sub_f32_e32 v147, v147, v250
	v_sub_f32_e32 v146, v146, v250
	v_pk_mul_f32 v[146:147], v[250:251], v[146:147] op_sel:[1,0]
	v_pk_mul_f32 v[144:145], v[250:251], v[144:145] op_sel:[1,0]
	v_pk_fma_f32 v[146:147], v[66:67], v[146:147], v[70:71]
	v_pk_fma_f32 v[144:145], v[64:65], v[144:145], v[68:69]
	v_pk_fma_f32 v[90:91], v[146:147], s[22:23], v[90:91] op_sel_hi:[1,0,1]
	v_pk_fma_f32 v[88:89], v[144:145], s[22:23], v[88:89] op_sel_hi:[1,0,1]
	s_waitcnt vmcnt(4)
	v_sub_f32_e32 v157, v157, v250
	v_sub_f32_e32 v156, v156, v250
	v_sub_f32_e32 v159, v159, v250
	v_sub_f32_e32 v158, v158, v250
	v_pk_mul_f32 v[158:159], v[250:251], v[158:159] op_sel:[1,0]
	v_pk_mul_f32 v[156:157], v[250:251], v[156:157] op_sel:[1,0]
	v_pk_fma_f32 v[158:159], v[58:59], v[158:159], v[62:63]
	v_pk_fma_f32 v[156:157], v[56:57], v[156:157], v[60:61]
	v_pk_fma_f32 v[86:87], v[158:159], s[22:23], v[86:87] op_sel_hi:[1,0,1]
	v_pk_fma_f32 v[84:85], v[156:157], s[22:23], v[84:85] op_sel_hi:[1,0,1]
	v_sub_f32_e32 v153, v153, v250
	v_sub_f32_e32 v152, v152, v250
	v_sub_f32_e32 v155, v155, v250
	v_sub_f32_e32 v154, v154, v250
	v_pk_mul_f32 v[154:155], v[250:251], v[154:155] op_sel:[1,0]
	v_pk_mul_f32 v[152:153], v[250:251], v[152:153] op_sel:[1,0]
	v_pk_fma_f32 v[154:155], v[50:51], v[154:155], v[54:55]
	v_pk_fma_f32 v[152:153], v[48:49], v[152:153], v[52:53]
	v_pk_fma_f32 v[82:83], v[154:155], s[22:23], v[82:83] op_sel_hi:[1,0,1]
	v_pk_fma_f32 v[80:81], v[152:153], s[22:23], v[80:81] op_sel_hi:[1,0,1]
	v_lshl_add_u64 v[248:249], s[46:47], 0, v[246:247]
	v_add_u32_e32 v206, 0x90, v172
	v_ashrrev_i32_e32 v207, 31, v206
	v_lshlrev_b64 v[208:209], 10, v[206:207]
	v_lshl_add_u64 v[208:209], v[208:209], 0, v[170:171]
	v_lshl_add_u64 v[206:207], v[206:207], 3, s[14:15]
	global_load_dwordx2 v[250:251], v[206:207], off
	v_lshlrev_b64 v[246:247], 2, v[208:209]
	v_lshl_add_u64 v[208:209], s[44:45], 0, v[246:247]
	global_load_dwordx4 v[144:147], v[208:209], off offset:16
	global_load_dwordx4 v[148:151], v[208:209], off
	global_load_dwordx4 v[152:155], v[208:209], off offset:528
	global_load_dwordx4 v[156:159], v[208:209], off offset:512
	global_store_dwordx4 v[248:249], v[92:95], off
	global_store_dwordx4 v[248:249], v[88:91], off offset:16
	global_store_dwordx4 v[248:249], v[84:87], off offset:512
	global_store_dwordx4 v[248:249], v[80:83], off offset:528
	s_waitcnt vmcnt(6)
	v_sub_f32_e32 v149, v149, v250
	v_sub_f32_e32 v148, v148, v250
	v_sub_f32_e32 v151, v151, v250
	v_sub_f32_e32 v150, v150, v250
	v_pk_mul_f32 v[150:151], v[250:251], v[150:151] op_sel:[1,0]
	v_pk_mul_f32 v[148:149], v[250:251], v[148:149] op_sel:[1,0]
	v_pk_fma_f32 v[150:151], v[74:75], v[150:151], v[78:79]
	v_pk_fma_f32 v[148:149], v[72:73], v[148:149], v[76:77]
	v_pk_fma_f32 v[46:47], v[150:151], s[22:23], v[46:47] op_sel_hi:[1,0,1]
	v_pk_fma_f32 v[44:45], v[148:149], s[22:23], v[44:45] op_sel_hi:[1,0,1]
	v_sub_f32_e32 v145, v145, v250
	v_sub_f32_e32 v144, v144, v250
	v_sub_f32_e32 v147, v147, v250
	v_sub_f32_e32 v146, v146, v250
	v_pk_mul_f32 v[146:147], v[250:251], v[146:147] op_sel:[1,0]
	v_pk_mul_f32 v[144:145], v[250:251], v[144:145] op_sel:[1,0]
	v_pk_fma_f32 v[146:147], v[66:67], v[146:147], v[70:71]
	v_pk_fma_f32 v[144:145], v[64:65], v[144:145], v[68:69]
	v_pk_fma_f32 v[42:43], v[146:147], s[22:23], v[42:43] op_sel_hi:[1,0,1]
	v_pk_fma_f32 v[40:41], v[144:145], s[22:23], v[40:41] op_sel_hi:[1,0,1]
	s_waitcnt vmcnt(4)
	v_sub_f32_e32 v157, v157, v250
	v_sub_f32_e32 v156, v156, v250
	v_sub_f32_e32 v159, v159, v250
	v_sub_f32_e32 v158, v158, v250
	v_pk_mul_f32 v[158:159], v[250:251], v[158:159] op_sel:[1,0]
	v_pk_mul_f32 v[156:157], v[250:251], v[156:157] op_sel:[1,0]
	v_pk_fma_f32 v[158:159], v[58:59], v[158:159], v[62:63]
	v_pk_fma_f32 v[156:157], v[56:57], v[156:157], v[60:61]
	v_pk_fma_f32 v[38:39], v[158:159], s[22:23], v[38:39] op_sel_hi:[1,0,1]
	v_pk_fma_f32 v[36:37], v[156:157], s[22:23], v[36:37] op_sel_hi:[1,0,1]
	v_sub_f32_e32 v153, v153, v250
	v_sub_f32_e32 v152, v152, v250
	v_sub_f32_e32 v155, v155, v250
	v_sub_f32_e32 v154, v154, v250
	v_pk_mul_f32 v[154:155], v[250:251], v[154:155] op_sel:[1,0]
	v_pk_mul_f32 v[152:153], v[250:251], v[152:153] op_sel:[1,0]
	v_pk_fma_f32 v[154:155], v[50:51], v[154:155], v[54:55]
	v_pk_fma_f32 v[152:153], v[48:49], v[152:153], v[52:53]
	v_pk_fma_f32 v[34:35], v[154:155], s[22:23], v[34:35] op_sel_hi:[1,0,1]
	v_pk_fma_f32 v[32:33], v[152:153], s[22:23], v[32:33] op_sel_hi:[1,0,1]
	v_lshl_add_u64 v[248:249], s[46:47], 0, v[246:247]
	v_add_u32_e32 v206, 0xa0, v172
	v_ashrrev_i32_e32 v207, 31, v206
	v_lshlrev_b64 v[208:209], 10, v[206:207]
	v_lshl_add_u64 v[208:209], v[208:209], 0, v[170:171]
	v_lshl_add_u64 v[206:207], v[206:207], 3, s[14:15]
	global_load_dwordx2 v[250:251], v[206:207], off
	v_lshlrev_b64 v[246:247], 2, v[208:209]
	v_lshl_add_u64 v[208:209], s[44:45], 0, v[246:247]
	global_load_dwordx4 v[144:147], v[208:209], off offset:16
	global_load_dwordx4 v[148:151], v[208:209], off
	global_load_dwordx4 v[152:155], v[208:209], off offset:528
	global_load_dwordx4 v[156:159], v[208:209], off offset:512
	global_store_dwordx4 v[248:249], v[44:47], off
	global_store_dwordx4 v[248:249], v[40:43], off offset:16
	global_store_dwordx4 v[248:249], v[36:39], off offset:512
	global_store_dwordx4 v[248:249], v[32:35], off offset:528
	s_waitcnt vmcnt(6)
	v_sub_f32_e32 v149, v149, v250
	v_sub_f32_e32 v148, v148, v250
	v_sub_f32_e32 v151, v151, v250
	v_sub_f32_e32 v150, v150, v250
	v_pk_mul_f32 v[150:151], v[250:251], v[150:151] op_sel:[1,0]
	v_pk_mul_f32 v[148:149], v[250:251], v[148:149] op_sel:[1,0]
	v_pk_fma_f32 v[150:151], v[74:75], v[150:151], v[78:79]
	v_pk_fma_f32 v[148:149], v[72:73], v[148:149], v[76:77]
	v_pk_fma_f32 v[30:31], v[150:151], s[22:23], v[30:31] op_sel_hi:[1,0,1]
	v_pk_fma_f32 v[28:29], v[148:149], s[22:23], v[28:29] op_sel_hi:[1,0,1]
	v_sub_f32_e32 v145, v145, v250
	v_sub_f32_e32 v144, v144, v250
	v_sub_f32_e32 v147, v147, v250
	v_sub_f32_e32 v146, v146, v250
	v_pk_mul_f32 v[146:147], v[250:251], v[146:147] op_sel:[1,0]
	v_pk_mul_f32 v[144:145], v[250:251], v[144:145] op_sel:[1,0]
	v_pk_fma_f32 v[146:147], v[66:67], v[146:147], v[70:71]
	v_pk_fma_f32 v[144:145], v[64:65], v[144:145], v[68:69]
	v_pk_fma_f32 v[26:27], v[146:147], s[22:23], v[26:27] op_sel_hi:[1,0,1]
	v_pk_fma_f32 v[24:25], v[144:145], s[22:23], v[24:25] op_sel_hi:[1,0,1]
	s_waitcnt vmcnt(4)
	v_sub_f32_e32 v157, v157, v250
	v_sub_f32_e32 v156, v156, v250
	v_sub_f32_e32 v159, v159, v250
	v_sub_f32_e32 v158, v158, v250
	v_pk_mul_f32 v[158:159], v[250:251], v[158:159] op_sel:[1,0]
	v_pk_mul_f32 v[156:157], v[250:251], v[156:157] op_sel:[1,0]
	v_pk_fma_f32 v[158:159], v[58:59], v[158:159], v[62:63]
	v_pk_fma_f32 v[156:157], v[56:57], v[156:157], v[60:61]
	v_pk_fma_f32 v[22:23], v[158:159], s[22:23], v[22:23] op_sel_hi:[1,0,1]
	v_pk_fma_f32 v[20:21], v[156:157], s[22:23], v[20:21] op_sel_hi:[1,0,1]
	v_sub_f32_e32 v153, v153, v250
	v_sub_f32_e32 v152, v152, v250
	v_sub_f32_e32 v155, v155, v250
	v_sub_f32_e32 v154, v154, v250
	v_pk_mul_f32 v[154:155], v[250:251], v[154:155] op_sel:[1,0]
	v_pk_mul_f32 v[152:153], v[250:251], v[152:153] op_sel:[1,0]
	v_pk_fma_f32 v[154:155], v[50:51], v[154:155], v[54:55]
	v_pk_fma_f32 v[152:153], v[48:49], v[152:153], v[52:53]
	v_pk_fma_f32 v[18:19], v[154:155], s[22:23], v[18:19] op_sel_hi:[1,0,1]
	v_pk_fma_f32 v[16:17], v[152:153], s[22:23], v[16:17] op_sel_hi:[1,0,1]
	v_lshl_add_u64 v[248:249], s[46:47], 0, v[246:247]
	v_add_u32_e32 v206, 0xb0, v172
	v_ashrrev_i32_e32 v207, 31, v206
	v_lshlrev_b64 v[208:209], 10, v[206:207]
	v_lshl_add_u64 v[208:209], v[208:209], 0, v[170:171]
	v_lshl_add_u64 v[206:207], v[206:207], 3, s[14:15]
	global_load_dwordx2 v[250:251], v[206:207], off
	v_lshlrev_b64 v[246:247], 2, v[208:209]
	v_lshl_add_u64 v[208:209], s[44:45], 0, v[246:247]
	global_load_dwordx4 v[144:147], v[208:209], off offset:16
	global_load_dwordx4 v[148:151], v[208:209], off
	global_load_dwordx4 v[152:155], v[208:209], off offset:528
	global_load_dwordx4 v[156:159], v[208:209], off offset:512
	global_store_dwordx4 v[248:249], v[28:31], off
	global_store_dwordx4 v[248:249], v[24:27], off offset:16
	global_store_dwordx4 v[248:249], v[20:23], off offset:512
	global_store_dwordx4 v[248:249], v[16:19], off offset:528
	s_waitcnt vmcnt(6)
	v_sub_f32_e32 v149, v149, v250
	v_sub_f32_e32 v148, v148, v250
	v_sub_f32_e32 v151, v151, v250
	v_sub_f32_e32 v150, v150, v250
	v_pk_mul_f32 v[150:151], v[250:251], v[150:151] op_sel:[1,0]
	v_pk_mul_f32 v[148:149], v[250:251], v[148:149] op_sel:[1,0]
	v_pk_fma_f32 v[150:151], v[74:75], v[150:151], v[78:79]
	v_pk_fma_f32 v[148:149], v[72:73], v[148:149], v[76:77]
	v_pk_fma_f32 v[14:15], v[150:151], s[22:23], v[14:15] op_sel_hi:[1,0,1]
	v_pk_fma_f32 v[12:13], v[148:149], s[22:23], v[12:13] op_sel_hi:[1,0,1]
	v_sub_f32_e32 v145, v145, v250
	v_sub_f32_e32 v144, v144, v250
	v_sub_f32_e32 v147, v147, v250
	v_sub_f32_e32 v146, v146, v250
	v_pk_mul_f32 v[146:147], v[250:251], v[146:147] op_sel:[1,0]
	v_pk_mul_f32 v[144:145], v[250:251], v[144:145] op_sel:[1,0]
	v_pk_fma_f32 v[146:147], v[66:67], v[146:147], v[70:71]
	v_pk_fma_f32 v[144:145], v[64:65], v[144:145], v[68:69]
	v_pk_fma_f32 v[10:11], v[146:147], s[22:23], v[10:11] op_sel_hi:[1,0,1]
	v_pk_fma_f32 v[8:9], v[144:145], s[22:23], v[8:9] op_sel_hi:[1,0,1]
	s_waitcnt vmcnt(4)
	v_sub_f32_e32 v157, v157, v250
	v_sub_f32_e32 v156, v156, v250
	v_sub_f32_e32 v159, v159, v250
	v_sub_f32_e32 v158, v158, v250
	v_pk_mul_f32 v[158:159], v[250:251], v[158:159] op_sel:[1,0]
	v_pk_mul_f32 v[156:157], v[250:251], v[156:157] op_sel:[1,0]
	v_pk_fma_f32 v[158:159], v[58:59], v[158:159], v[62:63]
	v_pk_fma_f32 v[156:157], v[56:57], v[156:157], v[60:61]
	v_pk_fma_f32 v[6:7], v[158:159], s[22:23], v[6:7] op_sel_hi:[1,0,1]
	v_pk_fma_f32 v[4:5], v[156:157], s[22:23], v[4:5] op_sel_hi:[1,0,1]
	v_sub_f32_e32 v153, v153, v250
	v_sub_f32_e32 v152, v152, v250
	v_sub_f32_e32 v155, v155, v250
	v_sub_f32_e32 v154, v154, v250
	v_pk_mul_f32 v[154:155], v[250:251], v[154:155] op_sel:[1,0]
	v_pk_mul_f32 v[152:153], v[250:251], v[152:153] op_sel:[1,0]
	v_pk_fma_f32 v[154:155], v[50:51], v[154:155], v[54:55]
	v_pk_fma_f32 v[152:153], v[48:49], v[152:153], v[52:53]
	v_pk_fma_f32 v[2:3], v[154:155], s[22:23], v[2:3] op_sel_hi:[1,0,1]
	v_pk_fma_f32 v[0:1], v[152:153], s[22:23], v[0:1] op_sel_hi:[1,0,1]
	v_lshl_add_u64 v[248:249], s[46:47], 0, v[246:247]
	global_store_dwordx4 v[248:249], v[12:15], off
	global_store_dwordx4 v[248:249], v[8:11], off offset:16
	global_store_dwordx4 v[248:249], v[4:7], off offset:512
	global_store_dwordx4 v[248:249], v[0:3], off offset:528
	s_cbranch_vccnz .LBB0_83
	s_andn2_b64 vcc, exec, s[48:49]
	s_cbranch_vccnz .LBB0_82
	s_barrier
	s_branch .LBB0_82

.LBB0_116:
	v_lshl_add_u32 v142, s89, 8, v144
	v_lshl_or_b32 v140, s88, 8, v146
	v_ashrrev_i32_e32 v143, 31, v142
	v_ashrrev_i32_e32 v141, 31, v140
	v_lshlrev_b64 v[138:139], 10, v[142:143]
	v_lshl_add_u64 v[138:139], v[138:139], 0, v[140:141]
	v_lshlrev_b64 v[138:139], 2, v[138:139]
	v_lshl_add_u64 v[160:161], s[44:45], 0, v[138:139]
	global_load_dwordx4 v[148:151], v[160:161], off offset:16
	global_load_dwordx4 v[152:155], v[160:161], off
	global_load_dwordx4 v[156:159], v[160:161], off offset:528
	s_nop 0
	global_load_dwordx4 v[160:163], v[160:161], off offset:512
	s_mov_b64 s[12:13], 0x80000
	s_mov_b64 s[28:29], -1
	s_and_b64 vcc, exec, s[40:41]
	s_waitcnt vmcnt(0)
	v_pk_fma_f32 v[124:125], v[152:153], s[22:23], v[124:125] op_sel_hi:[1,0,1]
	v_pk_fma_f32 v[126:127], v[154:155], s[22:23], v[126:127] op_sel_hi:[1,0,1]
	v_pk_fma_f32 v[120:121], v[148:149], s[22:23], v[120:121] op_sel_hi:[1,0,1]
	v_pk_fma_f32 v[122:123], v[150:151], s[22:23], v[122:123] op_sel_hi:[1,0,1]
	v_pk_fma_f32 v[116:117], v[160:161], s[22:23], v[116:117] op_sel_hi:[1,0,1]
	v_pk_fma_f32 v[118:119], v[162:163], s[22:23], v[118:119] op_sel_hi:[1,0,1]
	v_pk_fma_f32 v[112:113], v[156:157], s[22:23], v[112:113] op_sel_hi:[1,0,1]
	v_pk_fma_f32 v[114:115], v[158:159], s[22:23], v[114:115] op_sel_hi:[1,0,1]
	v_lshl_add_u64 v[248:249], s[46:47], 0, v[138:139]
	s_mov_b64 s[12:13], 0x10000
	v_lshl_add_u64 v[246:247], v[138:139], 0, s[12:13]
	v_lshl_add_u64 v[208:209], s[44:45], 0, v[246:247]
	global_load_dwordx4 v[148:151], v[208:209], off offset:16
	global_load_dwordx4 v[152:155], v[208:209], off
	global_load_dwordx4 v[156:159], v[208:209], off offset:528
	global_load_dwordx4 v[160:163], v[208:209], off offset:512
	global_store_dwordx4 v[248:249], v[124:127], off
	global_store_dwordx4 v[248:249], v[120:123], off offset:16
	global_store_dwordx4 v[248:249], v[116:119], off offset:512
	global_store_dwordx4 v[248:249], v[112:115], off offset:528
	s_waitcnt vmcnt(6)
	v_pk_fma_f32 v[108:109], v[152:153], s[22:23], v[108:109] op_sel_hi:[1,0,1]
	v_pk_fma_f32 v[110:111], v[154:155], s[22:23], v[110:111] op_sel_hi:[1,0,1]
	v_pk_fma_f32 v[104:105], v[148:149], s[22:23], v[104:105] op_sel_hi:[1,0,1]
	v_pk_fma_f32 v[106:107], v[150:151], s[22:23], v[106:107] op_sel_hi:[1,0,1]
	s_waitcnt vmcnt(4)
	v_pk_fma_f32 v[100:101], v[160:161], s[22:23], v[100:101] op_sel_hi:[1,0,1]
	v_pk_fma_f32 v[102:103], v[162:163], s[22:23], v[102:103] op_sel_hi:[1,0,1]
	v_pk_fma_f32 v[96:97], v[156:157], s[22:23], v[96:97] op_sel_hi:[1,0,1]
	v_pk_fma_f32 v[98:99], v[158:159], s[22:23], v[98:99] op_sel_hi:[1,0,1]
	v_lshl_add_u64 v[248:249], s[46:47], 0, v[246:247]
	s_mov_b64 s[12:13], 0x20000
	v_lshl_add_u64 v[246:247], v[138:139], 0, s[12:13]
	v_lshl_add_u64 v[208:209], s[44:45], 0, v[246:247]
	global_load_dwordx4 v[148:151], v[208:209], off offset:16
	global_load_dwordx4 v[152:155], v[208:209], off
	global_load_dwordx4 v[156:159], v[208:209], off offset:528
	global_load_dwordx4 v[160:163], v[208:209], off offset:512
	global_store_dwordx4 v[248:249], v[108:111], off
	global_store_dwordx4 v[248:249], v[104:107], off offset:16
	global_store_dwordx4 v[248:249], v[100:103], off offset:512
	global_store_dwordx4 v[248:249], v[96:99], off offset:528
	s_waitcnt vmcnt(6)
	v_pk_fma_f32 v[92:93], v[152:153], s[22:23], v[92:93] op_sel_hi:[1,0,1]
	v_pk_fma_f32 v[94:95], v[154:155], s[22:23], v[94:95] op_sel_hi:[1,0,1]
	v_pk_fma_f32 v[88:89], v[148:149], s[22:23], v[88:89] op_sel_hi:[1,0,1]
	v_pk_fma_f32 v[90:91], v[150:151], s[22:23], v[90:91] op_sel_hi:[1,0,1]
	s_waitcnt vmcnt(4)
	v_pk_fma_f32 v[84:85], v[160:161], s[22:23], v[84:85] op_sel_hi:[1,0,1]
	v_pk_fma_f32 v[86:87], v[162:163], s[22:23], v[86:87] op_sel_hi:[1,0,1]
	v_pk_fma_f32 v[80:81], v[156:157], s[22:23], v[80:81] op_sel_hi:[1,0,1]
	v_pk_fma_f32 v[82:83], v[158:159], s[22:23], v[82:83] op_sel_hi:[1,0,1]
	v_lshl_add_u64 v[248:249], s[46:47], 0, v[246:247]
	s_mov_b64 s[12:13], 0x30000
	v_lshl_add_u64 v[246:247], v[138:139], 0, s[12:13]
	v_lshl_add_u64 v[208:209], s[44:45], 0, v[246:247]
	global_load_dwordx4 v[148:151], v[208:209], off offset:16
	global_load_dwordx4 v[152:155], v[208:209], off
	global_load_dwordx4 v[156:159], v[208:209], off offset:528
	global_load_dwordx4 v[160:163], v[208:209], off offset:512
	global_store_dwordx4 v[248:249], v[92:95], off
	global_store_dwordx4 v[248:249], v[88:91], off offset:16
	global_store_dwordx4 v[248:249], v[84:87], off offset:512
	global_store_dwordx4 v[248:249], v[80:83], off offset:528
	s_waitcnt vmcnt(6)
	v_pk_fma_f32 v[76:77], v[152:153], s[22:23], v[76:77] op_sel_hi:[1,0,1]
	v_pk_fma_f32 v[78:79], v[154:155], s[22:23], v[78:79] op_sel_hi:[1,0,1]
	v_pk_fma_f32 v[72:73], v[148:149], s[22:23], v[72:73] op_sel_hi:[1,0,1]
	v_pk_fma_f32 v[74:75], v[150:151], s[22:23], v[74:75] op_sel_hi:[1,0,1]
	s_waitcnt vmcnt(4)
	v_pk_fma_f32 v[68:69], v[160:161], s[22:23], v[68:69] op_sel_hi:[1,0,1]
	v_pk_fma_f32 v[70:71], v[162:163], s[22:23], v[70:71] op_sel_hi:[1,0,1]
	v_pk_fma_f32 v[64:65], v[156:157], s[22:23], v[64:65] op_sel_hi:[1,0,1]
	v_pk_fma_f32 v[66:67], v[158:159], s[22:23], v[66:67] op_sel_hi:[1,0,1]
	v_lshl_add_u64 v[248:249], s[46:47], 0, v[246:247]
	s_mov_b64 s[12:13], 0x80000
	v_lshl_add_u64 v[246:247], v[138:139], 0, s[12:13]
	v_lshl_add_u64 v[208:209], s[44:45], 0, v[246:247]
	global_load_dwordx4 v[148:151], v[208:209], off offset:16
	global_load_dwordx4 v[152:155], v[208:209], off
	global_load_dwordx4 v[156:159], v[208:209], off offset:528
	global_load_dwordx4 v[160:163], v[208:209], off offset:512
	global_store_dwordx4 v[248:249], v[76:79], off
	global_store_dwordx4 v[248:249], v[72:75], off offset:16
	global_store_dwordx4 v[248:249], v[68:71], off offset:512
	global_store_dwordx4 v[248:249], v[64:67], off offset:528
	s_waitcnt vmcnt(6)
	v_pk_fma_f32 v[60:61], v[152:153], s[22:23], v[60:61] op_sel_hi:[1,0,1]
	v_pk_fma_f32 v[62:63], v[154:155], s[22:23], v[62:63] op_sel_hi:[1,0,1]
	v_pk_fma_f32 v[56:57], v[148:149], s[22:23], v[56:57] op_sel_hi:[1,0,1]
	v_pk_fma_f32 v[58:59], v[150:151], s[22:23], v[58:59] op_sel_hi:[1,0,1]
	s_waitcnt vmcnt(4)
	v_pk_fma_f32 v[52:53], v[160:161], s[22:23], v[52:53] op_sel_hi:[1,0,1]
	v_pk_fma_f32 v[54:55], v[162:163], s[22:23], v[54:55] op_sel_hi:[1,0,1]
	v_pk_fma_f32 v[48:49], v[156:157], s[22:23], v[48:49] op_sel_hi:[1,0,1]
	v_pk_fma_f32 v[50:51], v[158:159], s[22:23], v[50:51] op_sel_hi:[1,0,1]
	v_lshl_add_u64 v[248:249], s[46:47], 0, v[246:247]
	s_mov_b64 s[12:13], 0x90000
	v_lshl_add_u64 v[246:247], v[138:139], 0, s[12:13]
	v_lshl_add_u64 v[208:209], s[44:45], 0, v[246:247]
	global_load_dwordx4 v[148:151], v[208:209], off offset:16
	global_load_dwordx4 v[152:155], v[208:209], off
	global_load_dwordx4 v[156:159], v[208:209], off offset:528
	global_load_dwordx4 v[160:163], v[208:209], off offset:512
	global_store_dwordx4 v[248:249], v[60:63], off
	global_store_dwordx4 v[248:249], v[56:59], off offset:16
	global_store_dwordx4 v[248:249], v[52:55], off offset:512
	global_store_dwordx4 v[248:249], v[48:51], off offset:528
	s_waitcnt vmcnt(6)
	v_pk_fma_f32 v[44:45], v[152:153], s[22:23], v[44:45] op_sel_hi:[1,0,1]
	v_pk_fma_f32 v[46:47], v[154:155], s[22:23], v[46:47] op_sel_hi:[1,0,1]
	v_pk_fma_f32 v[40:41], v[148:149], s[22:23], v[40:41] op_sel_hi:[1,0,1]
	v_pk_fma_f32 v[42:43], v[150:151], s[22:23], v[42:43] op_sel_hi:[1,0,1]
	s_waitcnt vmcnt(4)
	v_pk_fma_f32 v[36:37], v[160:161], s[22:23], v[36:37] op_sel_hi:[1,0,1]
	v_pk_fma_f32 v[38:39], v[162:163], s[22:23], v[38:39] op_sel_hi:[1,0,1]
	v_pk_fma_f32 v[32:33], v[156:157], s[22:23], v[32:33] op_sel_hi:[1,0,1]
	v_pk_fma_f32 v[34:35], v[158:159], s[22:23], v[34:35] op_sel_hi:[1,0,1]
	v_lshl_add_u64 v[248:249], s[46:47], 0, v[246:247]
	s_mov_b64 s[12:13], 0xa0000
	v_lshl_add_u64 v[246:247], v[138:139], 0, s[12:13]
	v_lshl_add_u64 v[208:209], s[44:45], 0, v[246:247]
	global_load_dwordx4 v[148:151], v[208:209], off offset:16
	global_load_dwordx4 v[152:155], v[208:209], off
	global_load_dwordx4 v[156:159], v[208:209], off offset:528
	global_load_dwordx4 v[160:163], v[208:209], off offset:512
	global_store_dwordx4 v[248:249], v[44:47], off
	global_store_dwordx4 v[248:249], v[40:43], off offset:16
	global_store_dwordx4 v[248:249], v[36:39], off offset:512
	global_store_dwordx4 v[248:249], v[32:35], off offset:528
	s_waitcnt vmcnt(6)
	v_pk_fma_f32 v[28:29], v[152:153], s[22:23], v[28:29] op_sel_hi:[1,0,1]
	v_pk_fma_f32 v[30:31], v[154:155], s[22:23], v[30:31] op_sel_hi:[1,0,1]
	v_pk_fma_f32 v[24:25], v[148:149], s[22:23], v[24:25] op_sel_hi:[1,0,1]
	v_pk_fma_f32 v[26:27], v[150:151], s[22:23], v[26:27] op_sel_hi:[1,0,1]
	s_waitcnt vmcnt(4)
	v_pk_fma_f32 v[20:21], v[160:161], s[22:23], v[20:21] op_sel_hi:[1,0,1]
	v_pk_fma_f32 v[22:23], v[162:163], s[22:23], v[22:23] op_sel_hi:[1,0,1]
	v_pk_fma_f32 v[16:17], v[156:157], s[22:23], v[16:17] op_sel_hi:[1,0,1]
	v_pk_fma_f32 v[18:19], v[158:159], s[22:23], v[18:19] op_sel_hi:[1,0,1]
	v_lshl_add_u64 v[248:249], s[46:47], 0, v[246:247]
	s_mov_b64 s[12:13], 0xb0000
	v_lshl_add_u64 v[246:247], v[138:139], 0, s[12:13]
	v_lshl_add_u64 v[208:209], s[44:45], 0, v[246:247]
	global_load_dwordx4 v[148:151], v[208:209], off offset:16
	global_load_dwordx4 v[152:155], v[208:209], off
	global_load_dwordx4 v[156:159], v[208:209], off offset:528
	global_load_dwordx4 v[160:163], v[208:209], off offset:512
	global_store_dwordx4 v[248:249], v[28:31], off
	global_store_dwordx4 v[248:249], v[24:27], off offset:16
	global_store_dwordx4 v[248:249], v[20:23], off offset:512
	global_store_dwordx4 v[248:249], v[16:19], off offset:528
	s_waitcnt vmcnt(6)
	v_pk_fma_f32 v[12:13], v[152:153], s[22:23], v[12:13] op_sel_hi:[1,0,1]
	v_pk_fma_f32 v[14:15], v[154:155], s[22:23], v[14:15] op_sel_hi:[1,0,1]
	v_pk_fma_f32 v[8:9], v[148:149], s[22:23], v[8:9] op_sel_hi:[1,0,1]
	v_pk_fma_f32 v[10:11], v[150:151], s[22:23], v[10:11] op_sel_hi:[1,0,1]
	s_waitcnt vmcnt(4)
	v_pk_fma_f32 v[4:5], v[160:161], s[22:23], v[4:5] op_sel_hi:[1,0,1]
	v_pk_fma_f32 v[6:7], v[162:163], s[22:23], v[6:7] op_sel_hi:[1,0,1]
	v_pk_fma_f32 v[0:1], v[156:157], s[22:23], v[0:1] op_sel_hi:[1,0,1]
	v_pk_fma_f32 v[2:3], v[158:159], s[22:23], v[2:3] op_sel_hi:[1,0,1]
	v_lshl_add_u64 v[248:249], s[46:47], 0, v[246:247]
	global_store_dwordx4 v[248:249], v[12:15], off
	global_store_dwordx4 v[248:249], v[8:11], off offset:16
	global_store_dwordx4 v[248:249], v[4:7], off offset:512
	global_store_dwordx4 v[248:249], v[0:3], off offset:528
	s_cbranch_vccnz .LBB0_106
	s_andn2_b64 vcc, exec, s[50:51]
	s_cbranch_vccnz .LBB0_105
	s_barrier
	s_branch .LBB0_105
